# one static s_setprio 1 for waves 4-7 at kernel entry, no per-segment priority flips
# speedup vs baseline: 1.0067x; 1.0067x over previous
; #define LAS __attribute__((address_space(3)))
; __global__ void __launch_bounds__(512, 2) fwd(Args args) {
;     __shared__ __attribute__((aligned(16))) unsigned char lds_raw[LDS_BYTES];
;     LAS unsigned char* lds = (LAS unsigned char*)lds_raw;
;     volatile LAS unsigned* MISC = (volatile LAS unsigned*)(lds + MISC_OFF);
;     const int tid = threadIdx.x, lane = tid & 63, wave = __builtin_amdgcn_readfirstlane(tid >> 6);
;     const int G = gridDim.x, bx = blockIdx.x; const int vcu = (G % 8 == 0) ? (bx % 8) * (G / 8) + bx / 8 : bx;
;     unsigned char* ws = args.ws;
;     unsigned* ctl = (unsigned*)(ws + WS_CTL);
;     if (tid < 32) MISC[tid] = 0u;
_Z3fwd4Args:
	v_readfirstlane_b32 s32, v0
	s_nop 3
	s_lshr_b32 s32, s32, 8
	s_cmp_eq_u32 s32, 1
	s_cbranch_scc0 .Lprio_done
	s_setprio 1
.Lprio_done:
	s_load_dword s84, s[0:1], 0xf8
	s_load_dwordx4 s[88:91], s[0:1], 0xe0
	s_load_dwordx8 s[4:11], s[0:1], 0xc0
	s_mov_b32 s82, s2
	s_add_u32 s2, s0, 0xf8
	s_addc_u32 s3, s1, 0
	s_mov_b32 s33, s82
	s_waitcnt lgkmcnt(0)
	v_writelane_b32 v250, s4, 0
	s_nop 1
	v_writelane_b32 v250, s5, 1
	v_writelane_b32 v250, s6, 2
	v_writelane_b32 v250, s7, 3
	v_writelane_b32 v250, s8, 4
	v_writelane_b32 v250, s9, 5
	v_writelane_b32 v250, s10, 6
	v_writelane_b32 v250, s11, 7
	v_writelane_b32 v250, s2, 8
	s_nop 1
	v_writelane_b32 v250, s3, 9
	s_and_b32 s2, s84, 7
	s_cmp_lg_u32 s2, 0
	s_cbranch_scc0 .LBB0_80
	s_load_dwordx2 s[86:87], s[0:1], 0xf0
	v_cmp_gt_u32_e32 vcc, 32, v0
	s_and_saveexec_b64 s[4:5], vcc
